# P1: next unit As[1][1] staged at epilogue entry; first K iteration after an epilogue skips 3 already-satisfied vmcnt waits (stores drain under MFMA)
# speedup vs baseline: 1.0054x; 1.0054x over previous
; #define PG8_STAGE(bufoff, gbase, voff) do { _Pragma("unroll") for (int _i = 0; _i < 2; ++_i) \
;         __builtin_amdgcn_global_load_lds((const unsigned*)((const char*)(gbase) + (voff)[_i]), (PG8_LAS unsigned*)(lds + (bufoff) + ldsw + _i * 8192), 16, 0, 0); } while (0)
; #define PG8_WAIT_V(n) asm volatile("s_waitcnt vmcnt(" #n ")" ::: "memory")
; #define PG8_BAR __builtin_amdgcn_s_barrier()
;     __host__ __device__ bool next(int i, Unit& u) const {
;         const long L = (long)i * G + c; if (L >= nwg) return false;
;         int wgid = (int)L; { const int q = nwg / NXCD, r = nwg % NXCD, xcd = wgid % NXCD, off = wgid / NXCD; wgid = (xcd < r ? xcd * (q + 1) : r * (q + 1) + (xcd - r) * q) + off; }
;         const int nig = WGM * nN, gid = wgid / nig, fm = gid * WGM, gsz = (nM - fm) < WGM ? (nM - fm) : WGM;
;         u.pm = fm + ((wgid % nig) % gsz); u.pn = (wgid % nig) / gsz; return true;
;     }
; template <class Epi, class Sched, bool ALIGN_EPI = false, bool SP2 = false>
; __device__ __forceinline__ void gemm_phase(PG8_LAS unsigned char* lds, const Gemm g, const Sched& S, const Epi& E) {
;     ...
;     if constexpr (SP2) {
;         PG8_STAGE(PG8_SB(0, 0), cB, voffB); PG8_STAGE(PG8_SB(0, 1), cB + hstep, voffB); PG8_STAGE(PG8_SA(0, 0), cA, voffA); PG8_STAGE(PG8_SA(0, 1), cA + hstep, voffA);
;         if (wr == 1) PG8_BAR;
;         PG8_WAIT_V(2); PG8_BAR;
;         PG8_STAGE(PG8_SB(1, 0), cB + kstep, voffB); PG8_STAGE(PG8_SA(1, 0), cA + kstep, voffA); PG8_STAGE(PG8_SB(1, 1), cB + hstep + kstep, voffB);
;         PG8_WAIT_V(6); PG8_BAR;
.LBB0_194:
	s_cmp_lt_i32 s66, 2
	s_cselect_b64 s[0:1], -1, 0
	s_add_u32 s80, s64, 0x6f00000
	s_addc_u32 s81, s65, 0
	s_add_u32 s84, s64, 0xaf00000
	s_addc_u32 s85, s65, 0
	s_and_b64 s[6:7], s[0:1], s[2:3]
	s_andn2_b64 vcc, exec, s[6:7]
	s_cbranch_vccnz .LBB0_211
	s_mov_b32 s100, 0
	s_cmpk_gt_i32 s77, 0xaff
	v_readfirstlane_b32 s3, v220
	s_cbranch_scc1 .LBB0_211
	v_lshrrev_b32_e32 v0, 5, v220
	v_lshrrev_b32_e32 v2, 1, v220
	v_and_b32_e32 v0, 4, v0
	v_bfe_u32 v1, v220, 2, 2
	v_and_b32_e32 v11, 24, v2
	v_or3_b32 v0, v0, v1, v11
	v_lshlrev_b32_e32 v1, 4, v220
	v_add_u32_e32 v8, 0x2000, v1
	v_lshrrev_b32_e32 v2, 7, v8
	s_movk_i32 s1, 0xe0
	v_and_b32_e32 v4, 32, v220
	v_and_or_b32 v3, v2, s1, v0
	v_bitop3_b32 v9, v1, v4, 48 bitop3:0x6c
	v_and_b32_e32 v10, 64, v220
	v_bfe_u32 v12, v220, 2, 4
	s_movk_i32 s1, 0xf0
	v_or_b32_e32 v1, v9, v10
	v_and_or_b32 v2, v2, s1, v12
	v_lshl_or_b32 v130, v2, 12, v1
	v_lshrrev_b32_e32 v2, 3, v220
	s_movk_i32 s1, 0x60
	v_and_or_b32 v0, v2, s1, v0
	s_movk_i32 s1, 0x70
	v_lshl_or_b32 v132, v0, 12, v1
	v_and_or_b32 v0, v2, s1, v12
	s_ashr_i32 s1, s77, 31
	s_lshr_b32 s2, s1, 29
	s_add_i32 s2, s77, s2
	s_lshr_b32 s10, s3, 6
	s_ashr_i32 s4, s2, 3
	s_and_b32 s2, s2, -8
	s_lshr_b32 s12, s3, 8
	s_lshl_b32 s0, s10, 10
	s_sub_i32 s2, s77, s2
	s_cmp_lt_i32 s2, 0
	s_movk_i32 s28, 0x161
	s_cselect_b32 s5, s28, 0x160
	s_mul_i32 s2, s2, s5
	s_add_i32 s2, s2, s4
	s_mul_hi_i32 s4, s2, 0x2e8ba2e9
	s_lshr_b32 s5, s4, 31
	s_ashr_i32 s4, s4, 5
	s_add_i32 s4, s4, s5
	s_lshl_b32 s5, s4, 2
	s_mulk_i32 s4, 0xb0
	s_sub_i32 s4, s2, s4
	s_sext_i32_i16 s2, s4
	s_bfe_u32 s2, s2, 0x2001d
	s_add_i32 s8, s4, s2
	s_sext_i32_i16 s2, s8
	s_and_b32 s8, s8, 0xfffc
	s_sub_i32 s4, s4, s8
	s_sext_i32_i16 s4, s4
	s_lshr_b32 s2, s2, 2
	s_add_i32 s4, s5, s4
	s_ashr_i32 s5, s4, 31
	s_bfe_i64 s[14:15], s[2:3], 0x100000
	s_lshl_b64 s[8:9], s[4:5], 20
	s_lshl_b64 s[14:15], s[14:15], 20
	s_add_u32 s24, s86, s14
	s_addc_u32 s25, s87, s15
	s_add_i32 s29, s0, 0
	s_add_i32 m0, s29, 0x10000
	v_lshl_or_b32 v128, v3, 12, v1
	global_load_lds_dwordx4 v132, s[24:25]
	s_add_i32 m0, s29, 0x12000
	s_add_u32 s14, s24, 0x80000
	global_load_lds_dwordx4 v128, s[24:25]
	s_addc_u32 s15, s25, 0
	s_add_i32 m0, s29, 0x14000
	v_lshl_or_b32 v134, v0, 12, v1
	global_load_lds_dwordx4 v132, s[14:15]
	s_add_i32 m0, s29, 0x16000
	s_add_u32 s22, s80, s8
	s_addc_u32 s23, s81, s9
	s_add_i32 s30, s29, 0x2000
	global_load_lds_dwordx4 v128, s[14:15]
	s_mov_b32 m0, s29
	s_add_u32 s8, s22, 0x80000
	global_load_lds_dwordx4 v134, s[22:23]
	s_mov_b32 m0, s30
	s_addc_u32 s9, s23, 0
	s_add_i32 s31, s29, 0x4000
	global_load_lds_dwordx4 v130, s[22:23]
	s_mov_b32 m0, s31
	s_add_i32 s33, s29, 0x6000
	global_load_lds_dwordx4 v134, s[8:9]
	s_mov_b32 m0, s33
	v_mov_b32_e32 v133, 0
	global_load_lds_dwordx4 v130, s[8:9]
	v_mov_b32_e32 v129, v133
	v_mov_b32_e32 v135, v133
	v_mov_b32_e32 v131, v133
	s_cmp_eq_u32 s12, 1
	s_mov_b32 s34, 0
	v_lshl_add_u64 v[6:7], s[24:25], 0, v[132:133]
	v_lshl_add_u64 v[4:5], s[24:25], 0, v[128:129]
	v_lshl_add_u64 v[0:1], s[22:23], 0, v[134:135]
	s_cselect_b64 s[8:9], -1, 0
	s_cmp_lg_u32 s12, 1
	v_lshl_add_u64 v[2:3], s[22:23], 0, v[130:131]
	s_cbranch_scc1 .LBB0_198
	s_barrier

; #define PG8_STAGE(bufoff, gbase, voff) do { _Pragma("unroll") for (int _i = 0; _i < 2; ++_i) \
;         __builtin_amdgcn_global_load_lds((const unsigned*)((const char*)(gbase) + (voff)[_i]), (PG8_LAS unsigned*)(lds + (bufoff) + ldsw + _i * 8192), 16, 0, 0); } while (0)
; #define PG8_LDA(dst, b, h) do { _Pragma("unroll") for (int m = 0; m < 4; ++m) _Pragma("unroll") for (int k = 0; k < 2; ++k) dst[m][k] = *(const PG8_LAS bf16x8*)(lds + PG8_SA(b, h) + aoff + m * 2048 + k * 1024); } while (0)
; #define PG8_LDB(dst, b, h) do { _Pragma("unroll") for (int n = 0; n < 2; ++n) _Pragma("unroll") for (int k = 0; k < 2; ++k) dst[n][k] = *(const PG8_LAS bf16x8*)(lds + PG8_SB(b, h) + boff + n * 2048 + k * 1024); } while (0)
; #define PG8_MMA(ai, bj, At, Bt) do { __builtin_amdgcn_s_setprio(1); _Pragma("unroll") for (int m = 0; m < 4; ++m) _Pragma("unroll") for (int n = 0; n < 2; ++n) _Pragma("unroll") for (int k = 0; k < 2; ++k) \
;         acc[ai][bj][m][n] = __builtin_amdgcn_mfma_f32_16x16x32_bf16(Bt[n][k], At[m][k], acc[ai][bj][m][n], 0, 0, 0); __builtin_amdgcn_s_setprio(0); } while (0)
; #define PG8_WAIT_V(n) asm volatile("s_waitcnt vmcnt(" #n ")" ::: "memory")
; #define PG8_WAIT_L(n) asm volatile("s_waitcnt lgkmcnt(" #n ")" ::: "memory")
; #define PG8_BAR __builtin_amdgcn_s_barrier()
; #define PG8_SCHED __builtin_amdgcn_sched_barrier(0)
; template <class Epi, class Sched, bool ALIGN_EPI = false, bool SP2 = false>
; __device__ __forceinline__ void gemm_phase(PG8_LAS unsigned char* lds, const Gemm g, const Sched& S, const Epi& E) {
;     ...
;             PG8_LDB(B0, 0, 0); PG8_LDB(B1, 0, 1); PG8_SCHED; PG8_LDA(At, 0, 0); PG8_STAGE(PG8_SA(1, 1), a1 + hstep, voffA);
;             PG8_WAIT_V(8); PG8_WAIT_L(0); PG8_BAR; PG8_MMA(0, 0, At, B0); PG8_MMA(0, 1, At, B1); PG8_BAR; PG8_SCHED;
;             PG8_LDA(At, 0, 1); PG8_STAGE(PG8_SB(0, 0), b2, voffB); PG8_STAGE(PG8_SB(0, 1), b2 + hstep, voffB); PG8_STAGE(PG8_SA(0, 0), a2, voffA);
;             PG8_WAIT_V(8); PG8_WAIT_L(0); PG8_BAR; PG8_MMA(1, 0, At, B0); PG8_MMA(1, 1, At, B1); PG8_BAR; PG8_SCHED;
.LBB0_204:
	ds_read_b128 v[152:155], v147
	ds_read_b128 v[156:159], v147 offset:1024
	ds_read_b128 v[160:163], v147 offset:2048
	ds_read_b128 v[164:167], v147 offset:3072
	ds_read_b128 v[168:171], v148
	ds_read_b128 v[172:175], v148 offset:1024
	ds_read_b128 v[176:179], v148 offset:2048
	ds_read_b128 v[180:183], v148 offset:3072
	s_add_u32 s24, s22, 0xfff80080
	s_addc_u32 s25, s23, -1
	s_cmp_eq_u32 s51, 28
	s_cselect_b32 s27, s17, s25
	s_cselect_b32 s26, s47, s24
	s_cselect_b32 s25, s15, s50
	s_cselect_b32 s24, s48, s49
	v_lshl_add_u64 v[218:219], s[22:23], 0, v[136:137]
	s_add_i32 m0, s29, 0xc000
	ds_read_b128 v[184:187], v149
	ds_read_b128 v[188:191], v149 offset:1024
	ds_read_b128 v[192:195], v149 offset:2048
	ds_read_b128 v[196:199], v149 offset:3072
	ds_read_b128 v[200:203], v149 offset:4096
	ds_read_b128 v[206:209], v149 offset:5120
	ds_read_b128 v[210:213], v149 offset:6144
	ds_read_b128 v[214:217], v149 offset:7168
	s_cmp_lg_u32 s100, 0
	s_cbranch_scc1 .Lgr_p1_0
	global_load_lds_dwordx4 v[218:219], off
	v_lshl_add_u64 v[218:219], s[22:23], 0, v[138:139]
	s_add_i32 m0, s29, 0xe000
	s_nop 0
	global_load_lds_dwordx4 v[218:219], off
	s_waitcnt vmcnt(8)
.Lgr_p1_0:
	s_waitcnt lgkmcnt(0)
	s_barrier
	s_setprio 1
	s_waitcnt lgkmcnt(0)
	v_mfma_f32_16x16x32_bf16 v[116:119], v[152:155], v[184:187], v[116:119]
	v_mfma_f32_16x16x32_bf16 v[112:115], v[160:163], v[184:187], v[112:115]
	v_mfma_f32_16x16x32_bf16 v[108:111], v[152:155], v[192:195], v[108:111]
	v_mfma_f32_16x16x32_bf16 v[100:103], v[160:163], v[192:195], v[100:103]
	v_mfma_f32_16x16x32_bf16 v[92:95], v[152:155], v[200:203], v[92:95]
	v_mfma_f32_16x16x32_bf16 v[84:87], v[160:163], v[200:203], v[84:87]
	v_mfma_f32_16x16x32_bf16 v[76:79], v[152:155], v[210:213], v[76:79]
	v_mfma_f32_16x16x32_bf16 v[68:71], v[160:163], v[210:213], v[68:71]
	v_mfma_f32_16x16x32_bf16 v[116:119], v[156:159], v[188:191], v[116:119]
	v_mfma_f32_16x16x32_bf16 v[112:115], v[164:167], v[188:191], v[112:115]
	v_mfma_f32_16x16x32_bf16 v[108:111], v[156:159], v[196:199], v[108:111]
	v_mfma_f32_16x16x32_bf16 v[100:103], v[164:167], v[196:199], v[100:103]
	v_mfma_f32_16x16x32_bf16 v[92:95], v[156:159], v[206:209], v[92:95]
	v_mfma_f32_16x16x32_bf16 v[84:87], v[164:167], v[206:209], v[84:87]
	v_mfma_f32_16x16x32_bf16 v[76:79], v[156:159], v[214:217], v[76:79]
	v_mfma_f32_16x16x32_bf16 v[68:71], v[164:167], v[214:217], v[68:71]
	s_setprio 0
	s_setprio 1
	v_mfma_f32_16x16x32_bf16 v[124:127], v[168:171], v[184:187], v[124:127]
	v_mfma_f32_16x16x32_bf16 v[120:123], v[176:179], v[184:187], v[120:123]
	v_mfma_f32_16x16x32_bf16 v[104:107], v[168:171], v[192:195], v[104:107]
	v_mfma_f32_16x16x32_bf16 v[96:99], v[176:179], v[192:195], v[96:99]
	v_mfma_f32_16x16x32_bf16 v[88:91], v[168:171], v[200:203], v[88:91]
	v_mfma_f32_16x16x32_bf16 v[80:83], v[176:179], v[200:203], v[80:83]
	v_mfma_f32_16x16x32_bf16 v[72:75], v[168:171], v[210:213], v[72:75]
	v_mfma_f32_16x16x32_bf16 v[64:67], v[176:179], v[210:213], v[64:67]
	v_mfma_f32_16x16x32_bf16 v[124:127], v[172:175], v[188:191], v[124:127]
	v_mfma_f32_16x16x32_bf16 v[120:123], v[180:183], v[188:191], v[120:123]
	v_mfma_f32_16x16x32_bf16 v[104:107], v[172:175], v[196:199], v[104:107]
	v_mfma_f32_16x16x32_bf16 v[96:99], v[180:183], v[196:199], v[96:99]
	v_mfma_f32_16x16x32_bf16 v[88:91], v[172:175], v[206:209], v[88:91]
	v_mfma_f32_16x16x32_bf16 v[80:83], v[180:183], v[206:209], v[80:83]
	v_mfma_f32_16x16x32_bf16 v[72:75], v[172:175], v[214:217], v[72:75]
	v_mfma_f32_16x16x32_bf16 v[64:67], v[180:183], v[214:217], v[64:67]
	s_setprio 0
	s_barrier
	s_add_i32 s52, s43, s0
	v_lshl_add_u64 v[218:219], s[24:25], 0, v[132:133]
	s_mov_b32 m0, s52
	ds_read_b128 v[184:187], v149 offset:16384
	ds_read_b128 v[188:191], v149 offset:17408
	ds_read_b128 v[192:195], v149 offset:18432
	ds_read_b128 v[196:199], v149 offset:19456
	ds_read_b128 v[200:203], v149 offset:20480
	ds_read_b128 v[206:209], v149 offset:21504
	ds_read_b128 v[210:213], v149 offset:22528
	ds_read_b128 v[214:217], v149 offset:23552
	global_load_lds_dwordx4 v[218:219], off
	s_add_i32 m0, s52, 0x2000
	s_add_u32 s52, s24, 0x80000
	v_lshl_add_u64 v[222:223], s[24:25], 0, v[128:129]
	s_addc_u32 s53, s25, 0
	s_add_i32 s54, s44, s0
	global_load_lds_dwordx4 v[222:223], off
	v_lshl_add_u64 v[224:225], s[52:53], 0, v[132:133]
	s_mov_b32 m0, s54
	v_lshl_add_u64 v[226:227], s[26:27], 0, v[130:131]
	global_load_lds_dwordx4 v[224:225], off
	v_lshl_add_u64 v[224:225], s[52:53], 0, v[128:129]
	s_add_i32 m0, s54, 0x2000
	s_nop 0
	global_load_lds_dwordx4 v[224:225], off
	v_lshl_add_u64 v[224:225], s[26:27], 0, v[134:135]
	s_mov_b32 m0, s29
	s_nop 0
	global_load_lds_dwordx4 v[224:225], off
	s_mov_b32 m0, s30
	s_nop 0
	global_load_lds_dwordx4 v[226:227], off
	s_cmp_lg_u32 s100, 0
	s_cbranch_scc1 .Lgr_p1_1
	s_waitcnt vmcnt(8)
; #define PG8_STAGE(bufoff, gbase, voff) do { _Pragma("unroll") for (int _i = 0; _i < 2; ++_i) \
;         __builtin_amdgcn_global_load_lds((const unsigned*)((const char*)(gbase) + (voff)[_i]), (PG8_LAS unsigned*)(lds + (bufoff) + ldsw + _i * 8192), 16, 0, 0); } while (0)
; #define PG8_LDA(dst, b, h) do { _Pragma("unroll") for (int m = 0; m < 4; ++m) _Pragma("unroll") for (int k = 0; k < 2; ++k) dst[m][k] = *(const PG8_LAS bf16x8*)(lds + PG8_SA(b, h) + aoff + m * 2048 + k * 1024); } while (0)
; #define PG8_LDB(dst, b, h) do { _Pragma("unroll") for (int n = 0; n < 2; ++n) _Pragma("unroll") for (int k = 0; k < 2; ++k) dst[n][k] = *(const PG8_LAS bf16x8*)(lds + PG8_SB(b, h) + boff + n * 2048 + k * 1024); } while (0)
; #define PG8_MMA(ai, bj, At, Bt) do { __builtin_amdgcn_s_setprio(1); _Pragma("unroll") for (int m = 0; m < 4; ++m) _Pragma("unroll") for (int n = 0; n < 2; ++n) _Pragma("unroll") for (int k = 0; k < 2; ++k) \
;         acc[ai][bj][m][n] = __builtin_amdgcn_mfma_f32_16x16x32_bf16(Bt[n][k], At[m][k], acc[ai][bj][m][n], 0, 0, 0); __builtin_amdgcn_s_setprio(0); } while (0)
; #define PG8_WAIT_V(n) asm volatile("s_waitcnt vmcnt(" #n ")" ::: "memory")
; #define PG8_WAIT_L(n) asm volatile("s_waitcnt lgkmcnt(" #n ")" ::: "memory")
; #define PG8_BAR __builtin_amdgcn_s_barrier()
; #define PG8_SCHED __builtin_amdgcn_sched_barrier(0)
; template <class Epi, class Sched, bool ALIGN_EPI = false, bool SP2 = false>
; __device__ __forceinline__ void gemm_phase(PG8_LAS unsigned char* lds, const Gemm g, const Sched& S, const Epi& E) {
;     ...
;             PG8_WAIT_V(8); PG8_WAIT_L(0); PG8_BAR; PG8_MMA(1, 0, At, B0); PG8_MMA(1, 1, At, B1); PG8_BAR; PG8_SCHED;
;             PG8_LDB(B0, 1, 0); PG8_LDB(B1, 1, 1); PG8_SCHED; PG8_LDA(At, 1, 0); PG8_STAGE(PG8_SA(0, 1), a2 + hstep, voffA);
;             PG8_WAIT_V(8); PG8_WAIT_L(0); PG8_BAR; PG8_MMA(0, 0, At, B0); PG8_MMA(0, 1, At, B1); PG8_BAR; PG8_SCHED;
.Lgr_p1_1:
	s_waitcnt lgkmcnt(0)
	s_barrier
	s_setprio 1
	s_waitcnt lgkmcnt(0)
	v_mfma_f32_16x16x32_bf16 v[60:63], v[152:155], v[184:187], v[60:63]
	v_mfma_f32_16x16x32_bf16 v[52:55], v[160:163], v[184:187], v[52:55]
	v_mfma_f32_16x16x32_bf16 v[44:47], v[152:155], v[192:195], v[44:47]
	v_mfma_f32_16x16x32_bf16 v[36:39], v[160:163], v[192:195], v[36:39]
	v_mfma_f32_16x16x32_bf16 v[28:31], v[152:155], v[200:203], v[28:31]
	v_mfma_f32_16x16x32_bf16 v[20:23], v[160:163], v[200:203], v[20:23]
	v_mfma_f32_16x16x32_bf16 v[12:15], v[152:155], v[210:213], v[12:15]
	v_mfma_f32_16x16x32_bf16 v[4:7], v[160:163], v[210:213], v[4:7]
	v_mfma_f32_16x16x32_bf16 v[60:63], v[156:159], v[188:191], v[60:63]
	v_mfma_f32_16x16x32_bf16 v[52:55], v[164:167], v[188:191], v[52:55]
	v_mfma_f32_16x16x32_bf16 v[44:47], v[156:159], v[196:199], v[44:47]
	v_mfma_f32_16x16x32_bf16 v[36:39], v[164:167], v[196:199], v[36:39]
	v_mfma_f32_16x16x32_bf16 v[28:31], v[156:159], v[206:209], v[28:31]
	v_mfma_f32_16x16x32_bf16 v[20:23], v[164:167], v[206:209], v[20:23]
	v_mfma_f32_16x16x32_bf16 v[12:15], v[156:159], v[214:217], v[12:15]
	v_mfma_f32_16x16x32_bf16 v[4:7], v[164:167], v[214:217], v[4:7]
	s_setprio 0
	s_setprio 1
	v_mfma_f32_16x16x32_bf16 v[56:59], v[168:171], v[184:187], v[56:59]
	v_mfma_f32_16x16x32_bf16 v[48:51], v[176:179], v[184:187], v[48:51]
	v_mfma_f32_16x16x32_bf16 v[40:43], v[168:171], v[192:195], v[40:43]
	v_mfma_f32_16x16x32_bf16 v[32:35], v[176:179], v[192:195], v[32:35]
	v_mfma_f32_16x16x32_bf16 v[24:27], v[168:171], v[200:203], v[24:27]
	v_mfma_f32_16x16x32_bf16 v[16:19], v[176:179], v[200:203], v[16:19]
	v_mfma_f32_16x16x32_bf16 v[8:11], v[168:171], v[210:213], v[8:11]
	v_mfma_f32_16x16x32_bf16 v[0:3], v[176:179], v[210:213], v[0:3]
	v_mfma_f32_16x16x32_bf16 v[56:59], v[172:175], v[188:191], v[56:59]
	v_mfma_f32_16x16x32_bf16 v[48:51], v[180:183], v[188:191], v[48:51]
	v_mfma_f32_16x16x32_bf16 v[40:43], v[172:175], v[196:199], v[40:43]
	v_mfma_f32_16x16x32_bf16 v[32:35], v[180:183], v[196:199], v[32:35]
	v_mfma_f32_16x16x32_bf16 v[24:27], v[172:175], v[206:209], v[24:27]
	v_mfma_f32_16x16x32_bf16 v[16:19], v[180:183], v[206:209], v[16:19]
	v_mfma_f32_16x16x32_bf16 v[8:11], v[172:175], v[214:217], v[8:11]
	v_mfma_f32_16x16x32_bf16 v[0:3], v[180:183], v[214:217], v[0:3]
	s_setprio 0
	s_barrier
	s_add_i32 s52, 0, 0x18000
	v_add_u32_e32 v151, s52, v145
	s_add_i32 s53, 0, 0x1c000
	ds_read_b128 v[152:155], v151
	ds_read_b128 v[156:159], v151 offset:1024
	ds_read_b128 v[160:163], v151 offset:2048
	ds_read_b128 v[164:167], v151 offset:3072
	v_add_u32_e32 v151, s53, v145
	ds_read_b128 v[168:171], v151
	ds_read_b128 v[172:175], v151 offset:1024
	ds_read_b128 v[176:179], v151 offset:2048
	ds_read_b128 v[180:183], v151 offset:3072
	s_add_u32 s26, s26, 0x80000
	s_addc_u32 s27, s27, 0
	s_mov_b32 m0, s31
	v_lshl_add_u64 v[228:229], s[26:27], 0, v[134:135]
	ds_read_b128 v[184:187], v149 offset:32768
	ds_read_b128 v[188:191], v149 offset:33792
	ds_read_b128 v[192:195], v149 offset:34816
	ds_read_b128 v[196:199], v149 offset:35840
	ds_read_b128 v[200:203], v149 offset:36864
	ds_read_b128 v[206:209], v149 offset:37888
	ds_read_b128 v[210:213], v149 offset:38912
	ds_read_b128 v[214:217], v149 offset:39936
	global_load_lds_dwordx4 v[228:229], off
	v_lshl_add_u64 v[228:229], s[26:27], 0, v[130:131]
	s_mov_b32 m0, s33
	s_nop 0
	global_load_lds_dwordx4 v[228:229], off
	s_cmp_lg_u32 s100, 0
	s_cbranch_scc1 .Lgr_p1_2
	s_waitcnt vmcnt(8)
.Lgr_p1_2:
	s_waitcnt lgkmcnt(0)
	s_barrier
	s_setprio 1
	s_waitcnt lgkmcnt(0)
	v_mfma_f32_16x16x32_bf16 v[116:119], v[152:155], v[184:187], v[116:119]
	v_mfma_f32_16x16x32_bf16 v[112:115], v[160:163], v[184:187], v[112:115]
	v_mfma_f32_16x16x32_bf16 v[108:111], v[152:155], v[192:195], v[108:111]
	v_mfma_f32_16x16x32_bf16 v[100:103], v[160:163], v[192:195], v[100:103]
	v_mfma_f32_16x16x32_bf16 v[92:95], v[152:155], v[200:203], v[92:95]
	v_mfma_f32_16x16x32_bf16 v[84:87], v[160:163], v[200:203], v[84:87]
	v_mfma_f32_16x16x32_bf16 v[76:79], v[152:155], v[210:213], v[76:79]
	v_mfma_f32_16x16x32_bf16 v[68:71], v[160:163], v[210:213], v[68:71]
	v_mfma_f32_16x16x32_bf16 v[116:119], v[156:159], v[188:191], v[116:119]
	v_mfma_f32_16x16x32_bf16 v[112:115], v[164:167], v[188:191], v[112:115]
	v_mfma_f32_16x16x32_bf16 v[108:111], v[156:159], v[196:199], v[108:111]
	v_mfma_f32_16x16x32_bf16 v[100:103], v[164:167], v[196:199], v[100:103]
	v_mfma_f32_16x16x32_bf16 v[92:95], v[156:159], v[206:209], v[92:95]
	v_mfma_f32_16x16x32_bf16 v[84:87], v[164:167], v[206:209], v[84:87]
	v_mfma_f32_16x16x32_bf16 v[76:79], v[156:159], v[214:217], v[76:79]
	v_mfma_f32_16x16x32_bf16 v[68:71], v[164:167], v[214:217], v[68:71]
	s_setprio 0
	s_setprio 1
	v_mfma_f32_16x16x32_bf16 v[124:127], v[168:171], v[184:187], v[124:127]
	v_mfma_f32_16x16x32_bf16 v[120:123], v[176:179], v[184:187], v[120:123]
	v_mfma_f32_16x16x32_bf16 v[104:107], v[168:171], v[192:195], v[104:107]
	v_mfma_f32_16x16x32_bf16 v[96:99], v[176:179], v[192:195], v[96:99]
	v_mfma_f32_16x16x32_bf16 v[88:91], v[168:171], v[200:203], v[88:91]
	v_mfma_f32_16x16x32_bf16 v[80:83], v[176:179], v[200:203], v[80:83]
	v_mfma_f32_16x16x32_bf16 v[72:75], v[168:171], v[210:213], v[72:75]
	v_mfma_f32_16x16x32_bf16 v[64:67], v[176:179], v[210:213], v[64:67]
	v_mfma_f32_16x16x32_bf16 v[124:127], v[172:175], v[188:191], v[124:127]
	v_mfma_f32_16x16x32_bf16 v[120:123], v[180:183], v[188:191], v[120:123]
	v_mfma_f32_16x16x32_bf16 v[104:107], v[172:175], v[196:199], v[104:107]
	v_mfma_f32_16x16x32_bf16 v[96:99], v[180:183], v[196:199], v[96:99]
	v_mfma_f32_16x16x32_bf16 v[88:91], v[172:175], v[206:209], v[88:91]
	v_mfma_f32_16x16x32_bf16 v[80:83], v[180:183], v[206:209], v[80:83]
	v_mfma_f32_16x16x32_bf16 v[72:75], v[172:175], v[214:217], v[72:75]
	v_mfma_f32_16x16x32_bf16 v[64:67], v[180:183], v[214:217], v[64:67]
	s_setprio 0
	s_barrier
; #define PG8_STAGE(bufoff, gbase, voff) do { _Pragma("unroll") for (int _i = 0; _i < 2; ++_i) \
;         __builtin_amdgcn_global_load_lds((const unsigned*)((const char*)(gbase) + (voff)[_i]), (PG8_LAS unsigned*)(lds + (bufoff) + ldsw + _i * 8192), 16, 0, 0); } while (0)
; #define PG8_LDA(dst, b, h) do { _Pragma("unroll") for (int m = 0; m < 4; ++m) _Pragma("unroll") for (int k = 0; k < 2; ++k) dst[m][k] = *(const PG8_LAS bf16x8*)(lds + PG8_SA(b, h) + aoff + m * 2048 + k * 1024); } while (0)
; #define PG8_WAIT_V(n) asm volatile("s_waitcnt vmcnt(" #n ")" ::: "memory")
; #define PG8_WAIT_L(n) asm volatile("s_waitcnt lgkmcnt(" #n ")" ::: "memory")
; #define PG8_BAR __builtin_amdgcn_s_barrier()
; template <class Epi, class Sched, bool ALIGN_EPI = false, bool SP2 = false>
; __device__ __forceinline__ void gemm_phase(PG8_LAS unsigned char* lds, const Gemm g, const Sched& S, const Epi& E) {
;     ...
;             PG8_WAIT_V(8); PG8_WAIT_L(0); PG8_BAR; PG8_MMA(0, 0, At, B0); PG8_MMA(0, 1, At, B1); PG8_BAR; PG8_SCHED;
;             PG8_LDA(At, 1, 1); PG8_STAGE(PG8_SB(1, 0), b3, voffB); PG8_STAGE(PG8_SB(1, 1), b3 + hstep, voffB); PG8_STAGE(PG8_SA(1, 0), a3, voffA);
;             PG8_WAIT_V(8); PG8_WAIT_L(0); PG8_BAR; PG8_MMA(1, 0, At, B0); PG8_MMA(1, 1, At, B1); PG8_BAR; PG8_SCHED;
;     __device__ __forceinline__ void operator()(const pg8::f32x4 (&acc)[2][2][4][2], const pg8::Unit& u, int wr, int wc, int fr, int fq) const {
;         const int col0 = u.pn * 128 + wc * 32 + 8 * fq, row0 = u.pm * 256 + wr * 64 + fr;
;         float rsv[2][4];
; #pragma unroll
;         for (int ai = 0; ai < 2; ++ai)
; #pragma unroll
;             for (int m = 0; m < 4; ++m) rsv[ai][m] = ss[row0 + ai * 128 + m * 16];
; #pragma unroll
;         for (int ai = 0; ai < 2; ++ai)
; #pragma unroll
;             for (int m = 0; m < 4; ++m) {
;                 const int row = row0 + ai * 128 + m * 16;
;                 const float rs = rsqrtf(rsv[ai][m] * (1.f / DM) + EPS), c1 = -rs * LOG2E, rs2 = rs * rs;
;                 u32x4 w;
; #pragma unroll
;                 for (int n = 0; n < 2; ++n) {
;                     const pg8::f32x4 g = acc[ai][0][m][n], up = acc[ai][1][m][n];
;                     float o4[4];
; #pragma unroll
;                     for (int k = 0; k < 4; ++k) o4[k] = (g[k] * up[k]) * (rs2 * __builtin_amdgcn_rcpf(1.f + __builtin_amdgcn_exp2f(g[k] * c1)));
	s_add_i32 s26, s52, s0
	v_lshl_add_u64 v[218:219], v[218:219], 0, s[10:11]
	s_mov_b32 m0, s26
	ds_read_b128 v[184:187], v149 offset:49152
	ds_read_b128 v[188:191], v149 offset:50176
	ds_read_b128 v[192:195], v149 offset:51200
	ds_read_b128 v[196:199], v149 offset:52224
	ds_read_b128 v[200:203], v149 offset:53248
	ds_read_b128 v[206:209], v149 offset:54272
	ds_read_b128 v[210:213], v149 offset:55296
	ds_read_b128 v[214:217], v149 offset:56320
	global_load_lds_dwordx4 v[218:219], off
	s_add_i32 m0, s26, 0x2000
	s_add_u32 s24, s24, 0x80080
	v_lshl_add_u64 v[218:219], v[222:223], 0, s[10:11]
	s_addc_u32 s25, s25, 0
	s_add_i32 s26, s53, s0
	global_load_lds_dwordx4 v[218:219], off
	v_lshl_add_u64 v[218:219], s[24:25], 0, v[132:133]
	s_mov_b32 m0, s26
	s_nop 0
	global_load_lds_dwordx4 v[218:219], off
	v_lshl_add_u64 v[218:219], s[24:25], 0, v[128:129]
	s_add_i32 m0, s26, 0x2000
	s_nop 0
	global_load_lds_dwordx4 v[218:219], off
	v_lshl_add_u64 v[218:219], v[224:225], 0, s[10:11]
	s_mov_b32 m0, s35
	s_nop 0
	global_load_lds_dwordx4 v[218:219], off
	v_lshl_add_u64 v[218:219], v[226:227], 0, s[10:11]
	s_mov_b32 m0, s40
	s_nop 0
	global_load_lds_dwordx4 v[218:219], off
	s_waitcnt vmcnt(8)
	s_waitcnt lgkmcnt(0)
	s_barrier
	s_setprio 1
	s_waitcnt lgkmcnt(0)
	v_mfma_f32_16x16x32_bf16 v[60:63], v[152:155], v[184:187], v[60:63]
	v_mfma_f32_16x16x32_bf16 v[52:55], v[160:163], v[184:187], v[52:55]
	v_mfma_f32_16x16x32_bf16 v[44:47], v[152:155], v[192:195], v[44:47]
	v_mfma_f32_16x16x32_bf16 v[36:39], v[160:163], v[192:195], v[36:39]
	v_mfma_f32_16x16x32_bf16 v[28:31], v[152:155], v[200:203], v[28:31]
	v_mfma_f32_16x16x32_bf16 v[20:23], v[160:163], v[200:203], v[20:23]
	v_mfma_f32_16x16x32_bf16 v[12:15], v[152:155], v[210:213], v[12:15]
	v_mfma_f32_16x16x32_bf16 v[4:7], v[160:163], v[210:213], v[4:7]
	v_mfma_f32_16x16x32_bf16 v[60:63], v[156:159], v[188:191], v[60:63]
	v_mfma_f32_16x16x32_bf16 v[52:55], v[164:167], v[188:191], v[52:55]
	v_mfma_f32_16x16x32_bf16 v[44:47], v[156:159], v[196:199], v[44:47]
	v_mfma_f32_16x16x32_bf16 v[36:39], v[164:167], v[196:199], v[36:39]
	v_mfma_f32_16x16x32_bf16 v[28:31], v[156:159], v[206:209], v[28:31]
	v_mfma_f32_16x16x32_bf16 v[20:23], v[164:167], v[206:209], v[20:23]
	v_mfma_f32_16x16x32_bf16 v[12:15], v[156:159], v[214:217], v[12:15]
	v_mfma_f32_16x16x32_bf16 v[4:7], v[164:167], v[214:217], v[4:7]
	s_setprio 0
	s_setprio 1
	v_mfma_f32_16x16x32_bf16 v[56:59], v[168:171], v[184:187], v[56:59]
	v_mfma_f32_16x16x32_bf16 v[48:51], v[176:179], v[184:187], v[48:51]
	v_mfma_f32_16x16x32_bf16 v[40:43], v[168:171], v[192:195], v[40:43]
	v_mfma_f32_16x16x32_bf16 v[32:35], v[176:179], v[192:195], v[32:35]
	v_mfma_f32_16x16x32_bf16 v[24:27], v[168:171], v[200:203], v[24:27]
	v_mfma_f32_16x16x32_bf16 v[16:19], v[176:179], v[200:203], v[16:19]
	v_mfma_f32_16x16x32_bf16 v[8:11], v[168:171], v[210:213], v[8:11]
	v_mfma_f32_16x16x32_bf16 v[0:3], v[176:179], v[210:213], v[0:3]
	v_mfma_f32_16x16x32_bf16 v[56:59], v[172:175], v[188:191], v[56:59]
	v_mfma_f32_16x16x32_bf16 v[48:51], v[180:183], v[188:191], v[48:51]
	v_mfma_f32_16x16x32_bf16 v[40:43], v[172:175], v[196:199], v[40:43]
	v_mfma_f32_16x16x32_bf16 v[32:35], v[180:183], v[196:199], v[32:35]
	v_mfma_f32_16x16x32_bf16 v[24:27], v[172:175], v[206:209], v[24:27]
	v_mfma_f32_16x16x32_bf16 v[16:19], v[180:183], v[206:209], v[16:19]
	v_mfma_f32_16x16x32_bf16 v[8:11], v[172:175], v[214:217], v[8:11]
	v_mfma_f32_16x16x32_bf16 v[0:3], v[180:183], v[214:217], v[0:3]
	s_setprio 0
	s_barrier
	s_mov_b32 s100, 0
	s_add_i32 s51, s51, 2
	s_add_u32 s22, s22, 0x100
	s_addc_u32 s23, s23, 0
	s_add_u32 s49, s49, 0x100
	s_addc_u32 s50, s50, 0
	s_cmp_gt_u32 s51, 29
	s_cbranch_scc0 .LBB0_204
	s_and_b64 vcc, exec, s[12:13]
	s_cbranch_vccz .LBB0_207
	s_barrier
.LBB0_207:
	s_add_u32 s98, s47, 0x80080
	s_addc_u32 s99, s17, 0
	v_lshl_add_u64 v[252:253], s[98:99], 0, v[136:137]
	s_add_i32 m0, s29, 0xc000
	s_nop 0
	global_load_lds_dwordx4 v[252:253], off
	v_lshl_add_u64 v[252:253], s[98:99], 0, v[138:139]
	s_add_i32 m0, s29, 0xe000
	s_nop 0
	global_load_lds_dwordx4 v[252:253], off
	s_mov_b32 s100, 1
	v_lshl_add_u32 v152, s4, 8, v144
	v_ashrrev_i32_e32 v153, 31, v152
	v_lshl_add_u64 v[154:155], v[152:153], 2, s[64:65]
	global_load_dword v151, v[154:155], off
	global_load_dword v168, v[154:155], off offset:64
	v_pk_mul_f32 v[158:159], v[118:119], v[126:127]
	v_pk_mul_f32 v[160:161], v[116:117], v[124:125]
	global_load_dword v173, v[154:155], off offset:128
	global_load_dword v174, v[154:155], off offset:192
	global_load_dword v175, v[154:155], off offset:512
	global_load_dword v176, v[154:155], off offset:576
	global_load_dword v126, v[154:155], off offset:640
	global_load_dword v124, v[154:155], off offset:704
	v_pk_mul_f32 v[164:165], v[112:113], v[120:121]
	v_mov_b64_e32 v[120:121], s[84:85]
	v_pk_mul_f32 v[166:167], v[110:111], v[106:107]
	v_lshl_or_b32 v156, s5, 7, v146
	v_pk_mul_f32 v[162:163], v[114:115], v[122:123]
	v_or_b32_e32 v127, 16, v152
	v_or_b32_e32 v170, 32, v152
	v_or_b32_e32 v171, 48, v152
	v_add_u32_e32 v172, 0x80, v152
	v_add_u32_e32 v125, 0x90, v152
	v_add_u32_e32 v123, 0xa0, v152
	v_add_u32_e32 v122, 0xb0, v152
	v_mad_i64_i32 v[152:153], s[4:5], v152, s46, v[120:121]
	v_ashrrev_i32_e32 v157, 31, v156
	v_pk_mul_f32 v[104:105], v[108:109], v[104:105]
	v_pk_mul_f32 v[98:99], v[102:103], v[98:99]
	v_pk_mul_f32 v[96:97], v[100:101], v[96:97]
	v_pk_mul_f32 v[90:91], v[94:95], v[90:91]
	v_pk_mul_f32 v[88:89], v[92:93], v[88:89]
	v_pk_mul_f32 v[82:83], v[86:87], v[82:83]
	v_pk_mul_f32 v[80:81], v[84:85], v[80:81]
	v_pk_mul_f32 v[74:75], v[78:79], v[74:75]
	v_pk_mul_f32 v[72:73], v[76:77], v[72:73]
	v_pk_mul_f32 v[66:67], v[70:71], v[66:67]
	v_pk_mul_f32 v[64:65], v[68:69], v[64:65]
	v_pk_mul_f32 v[58:59], v[62:63], v[58:59]
	v_pk_mul_f32 v[56:57], v[60:61], v[56:57]
	v_pk_mul_f32 v[50:51], v[54:55], v[50:51]
	v_pk_mul_f32 v[48:49], v[52:53], v[48:49]
	v_pk_mul_f32 v[42:43], v[46:47], v[42:43]
	v_pk_mul_f32 v[40:41], v[44:45], v[40:41]
	v_pk_mul_f32 v[34:35], v[38:39], v[34:35]
	v_pk_mul_f32 v[32:33], v[36:37], v[32:33]
	v_pk_mul_f32 v[26:27], v[30:31], v[26:27]
	v_pk_mul_f32 v[24:25], v[28:29], v[24:25]
	v_pk_mul_f32 v[18:19], v[22:23], v[18:19]
	v_pk_mul_f32 v[16:17], v[20:21], v[16:17]
	v_pk_mul_f32 v[10:11], v[14:15], v[10:11]
	v_pk_mul_f32 v[8:9], v[12:13], v[8:9]
	v_pk_mul_f32 v[2:3], v[6:7], v[2:3]
	v_pk_mul_f32 v[0:1], v[4:5], v[0:1]
	s_waitcnt vmcnt(0)
; __device__ __forceinline__ unsigned cvtpk(float lo, float hi) { f32x2_t v = {lo, hi}; bf16x2_t b = __builtin_convertvector(v, bf16x2_t); return __builtin_bit_cast(unsigned, b); }
;     __device__ __forceinline__ void operator()(const pg8::f32x4 (&acc)[2][2][4][2], const pg8::Unit& u, int wr, int wc, int fr, int fq) const {
;     ...
;             for (int m = 0; m < 4; ++m) rsv[ai][m] = ss[row0 + ai * 128 + m * 16];
; #pragma unroll
;         for (int ai = 0; ai < 2; ++ai)
; #pragma unroll
;             for (int m = 0; m < 4; ++m) {
;                 const int row = row0 + ai * 128 + m * 16;
;                 const float rs = rsqrtf(rsv[ai][m] * (1.f / DM) + EPS), c1 = -rs * LOG2E, rs2 = rs * rs;
;                 u32x4 w;
; #pragma unroll
;                 for (int n = 0; n < 2; ++n) {
;                     const pg8::f32x4 g = acc[ai][0][m][n], up = acc[ai][1][m][n];
;                     float o4[4];
; #pragma unroll
;                     for (int k = 0; k < 4; ++k) o4[k] = (g[k] * up[k]) * (rs2 * __builtin_amdgcn_rcpf(1.f + __builtin_amdgcn_exp2f(g[k] * c1)));
;                     w[2 * n] = cvtpk(o4[0], o4[1]); w[2 * n + 1] = cvtpk(o4[2], o4[3]);
;                 }
;                 *(u32x4*)(O + (size_t)row * FF + col0) = w;
;             }
	v_fmamk_f32 v106, v151, 0x3a000000, v150
	v_fmamk_f32 v107, v168, 0x3a000000, v150
	v_mul_f32_e32 v151, 0x4b800000, v106
	v_cmp_gt_f32_e32 vcc, s45, v106
	v_mul_f32_e32 v154, 0x4b800000, v107
	v_cmp_gt_f32_e64 s[4:5], s45, v107
	v_cndmask_b32_e32 v106, v106, v151, vcc
	v_rsq_f32_e32 v151, v106
	v_cndmask_b32_e64 v107, v107, v154, s[4:5]
	v_rsq_f32_e32 v154, v107
	v_lshlrev_b64 v[106:107], 1, v[156:157]
	v_mul_f32_e32 v155, 0x45800000, v151
	v_cndmask_b32_e32 v151, v151, v155, vcc
	v_mul_f32_e32 v156, 0x45800000, v154
	v_cndmask_b32_e64 v155, v154, v156, s[4:5]
	v_mul_f32_e32 v157, 0xbfb8aa3b, v151
	v_mul_f32_e32 v154, v151, v151
	v_mul_f32_e32 v151, 0xbfb8aa3b, v155
	v_mul_f32_e32 v116, v116, v157
	v_mul_f32_e32 v117, v117, v157
	v_mul_f32_e32 v118, v118, v157
	v_mul_f32_e32 v119, v119, v157
	v_mul_f32_e32 v112, v112, v157
	v_mul_f32_e32 v113, v113, v157
	v_mul_f32_e32 v114, v114, v157
	v_mul_f32_e32 v115, v115, v157
	v_mul_f32_e32 v110, v110, v151
	v_exp_f32_e32 v116, v116
	v_exp_f32_e32 v117, v117
	v_exp_f32_e32 v118, v118
	v_exp_f32_e32 v119, v119
	v_exp_f32_e32 v112, v112
	v_exp_f32_e32 v113, v113
	v_exp_f32_e32 v114, v114
	v_exp_f32_e32 v115, v115
	v_exp_f32_e32 v110, v110
	v_mul_f32_e32 v156, v155, v155
	v_mul_f32_e32 v155, v108, v151
	v_mul_f32_e32 v111, v111, v151
	v_exp_f32_e32 v155, v155
	v_exp_f32_e32 v169, v111
	v_add_f32_e32 v111, 1.0, v116
	v_add_f32_e32 v116, 1.0, v117
	v_add_f32_e32 v117, 1.0, v118
	v_add_f32_e32 v118, 1.0, v119
	v_add_f32_e32 v119, 1.0, v112
	v_add_f32_e32 v168, 1.0, v113
	v_add_f32_e32 v177, 1.0, v114
	v_add_f32_e32 v178, 1.0, v115
	v_add_f32_e32 v179, 1.0, v110
	v_rcp_f32_e32 v110, v111
	v_rcp_f32_e32 v111, v116
	v_rcp_f32_e32 v112, v117
	v_rcp_f32_e32 v113, v118
	v_rcp_f32_e32 v114, v119
	v_rcp_f32_e32 v115, v168
	v_rcp_f32_e32 v116, v177
	v_rcp_f32_e32 v117, v178
	v_mul_f32_e32 v157, v109, v151
	v_exp_f32_e32 v157, v157
	v_add_f32_e32 v155, 1.0, v155
	v_pk_mul_f32 v[110:111], v[154:155], v[110:111] op_sel_hi:[0,1]
	v_pk_mul_f32 v[112:113], v[154:155], v[112:113] op_sel_hi:[0,1]
	v_pk_mul_f32 v[114:115], v[154:155], v[114:115] op_sel_hi:[0,1]
	v_pk_mul_f32 v[116:117], v[154:155], v[116:117] op_sel_hi:[0,1]
	v_pk_mul_f32 v[110:111], v[160:161], v[110:111]
	v_pk_mul_f32 v[112:113], v[158:159], v[112:113]
	v_pk_mul_f32 v[114:115], v[164:165], v[114:115]
	v_pk_mul_f32 v[116:117], v[162:163], v[116:117]
	v_lshl_add_u64 v[152:153], v[152:153], 0, v[106:107]
	v_add_f32_e32 v157, 1.0, v157
	v_cvt_pk_bf16_f32 v110, v110, v111
	v_cvt_pk_bf16_f32 v111, v112, v113
	v_cvt_pk_bf16_f32 v112, v114, v115
	v_cvt_pk_bf16_f32 v113, v116, v117
	v_rcp_f32_e32 v118, v155
	v_rcp_f32_e32 v119, v157
	global_store_dwordx4 v[152:153], v[110:113], off
	v_rcp_f32_e32 v168, v179
	v_pk_mul_f32 v[108:109], v[156:157], v[118:119] op_sel_hi:[0,1]
	v_add_f32_e32 v110, 1.0, v169
	v_rcp_f32_e32 v169, v110
	v_pk_mul_f32 v[104:105], v[104:105], v[108:109]
	v_pk_mul_f32 v[108:109], v[156:157], v[168:169] op_sel_hi:[0,1]
	v_pk_mul_f32 v[110:111], v[166:167], v[108:109]
	v_cvt_pk_bf16_f32 v108, v104, v105
	v_mul_f32_e32 v104, v100, v151
	v_mul_f32_e32 v105, v101, v151
	v_exp_f32_e32 v104, v104
	v_exp_f32_e32 v105, v105
	v_cvt_pk_bf16_f32 v109, v110, v111
	v_mul_f32_e32 v110, v102, v151
	v_mul_f32_e32 v111, v103, v151
	v_exp_f32_e32 v110, v110
	v_exp_f32_e32 v111, v111
	v_add_f32_e32 v104, 1.0, v104
	v_add_f32_e32 v105, 1.0, v105
	v_rcp_f32_e32 v104, v104
	v_rcp_f32_e32 v105, v105
	v_add_f32_e32 v102, 1.0, v110
	v_add_f32_e32 v103, 1.0, v111
	v_rcp_f32_e32 v102, v102
	v_rcp_f32_e32 v103, v103
	v_pk_mul_f32 v[100:101], v[156:157], v[104:105] op_sel_hi:[0,1]
	v_pk_mul_f32 v[96:97], v[96:97], v[100:101]
	v_pk_mul_f32 v[100:101], v[156:157], v[102:103] op_sel_hi:[0,1]
	v_cvt_pk_bf16_f32 v110, v96, v97
	v_fmamk_f32 v96, v173, 0x3a000000, v150
	v_mul_f32_e32 v97, 0x4b800000, v96
	v_cmp_gt_f32_e32 vcc, s45, v96
	v_pk_mul_f32 v[98:99], v[98:99], v[100:101]
	s_nop 0
	v_cndmask_b32_e32 v96, v96, v97, vcc
	v_cvt_pk_bf16_f32 v111, v98, v99
	v_rsq_f32_e32 v98, v96
	v_mad_i64_i32 v[96:97], s[4:5], v127, s46, v[120:121]
	v_lshl_add_u64 v[96:97], v[96:97], 0, v[106:107]
	global_store_dwordx4 v[96:97], v[108:111], off
	v_mul_f32_e32 v96, 0x45800000, v98
	v_cndmask_b32_e32 v96, v98, v96, vcc
	v_mul_f32_e32 v97, 0xbfb8aa3b, v96
	v_mul_f32_e32 v98, v92, v97
	v_mul_f32_e32 v99, v93, v97
	v_exp_f32_e32 v98, v98
	v_exp_f32_e32 v99, v99
	v_mul_f32_e32 v100, v94, v97
	v_mul_f32_e32 v101, v95, v97
	v_exp_f32_e32 v100, v100
	v_exp_f32_e32 v101, v101
	v_add_f32_e32 v98, 1.0, v98
	v_add_f32_e32 v99, 1.0, v99
	v_rcp_f32_e32 v98, v98
	v_rcp_f32_e32 v99, v99
	v_add_f32_e32 v94, 1.0, v100
	v_add_f32_e32 v95, 1.0, v101
	v_rcp_f32_e32 v94, v94
	v_rcp_f32_e32 v95, v95
	v_mul_f32_e32 v96, v96, v96
	v_pk_mul_f32 v[92:93], v[96:97], v[98:99] op_sel_hi:[0,1]
	v_pk_mul_f32 v[88:89], v[88:89], v[92:93]
	v_pk_mul_f32 v[92:93], v[96:97], v[94:95] op_sel_hi:[0,1]
	v_cvt_pk_bf16_f32 v88, v88, v89
	v_mul_f32_e32 v89, v84, v97
	v_pk_mul_f32 v[90:91], v[90:91], v[92:93]
	v_exp_f32_e32 v92, v89
	v_mul_f32_e32 v89, v85, v97
	v_exp_f32_e32 v93, v89
	v_cvt_pk_bf16_f32 v89, v90, v91
	v_add_f32_e32 v90, 1.0, v92
	v_mul_f32_e32 v92, v86, v97
	v_add_f32_e32 v91, 1.0, v93
	v_mul_f32_e32 v93, v87, v97
	v_exp_f32_e32 v92, v92
	v_exp_f32_e32 v93, v93
	v_rcp_f32_e32 v90, v90
	v_rcp_f32_e32 v91, v91
	v_add_f32_e32 v86, 1.0, v92
	v_add_f32_e32 v87, 1.0, v93
	v_rcp_f32_e32 v86, v86
	v_rcp_f32_e32 v87, v87
	v_pk_mul_f32 v[84:85], v[96:97], v[90:91] op_sel_hi:[0,1]
	v_pk_mul_f32 v[80:81], v[80:81], v[84:85]
	v_pk_mul_f32 v[84:85], v[96:97], v[86:87] op_sel_hi:[0,1]
	v_cvt_pk_bf16_f32 v90, v80, v81
; __device__ __forceinline__ unsigned cvtpk(float lo, float hi) { f32x2_t v = {lo, hi}; bf16x2_t b = __builtin_convertvector(v, bf16x2_t); return __builtin_bit_cast(unsigned, b); }
;     __device__ __forceinline__ void operator()(const pg8::f32x4 (&acc)[2][2][4][2], const pg8::Unit& u, int wr, int wc, int fr, int fq) const {
;     ...
;         for (int ai = 0; ai < 2; ++ai)
; #pragma unroll
;             for (int m = 0; m < 4; ++m) {
;                 const int row = row0 + ai * 128 + m * 16;
;                 const float rs = rsqrtf(rsv[ai][m] * (1.f / DM) + EPS), c1 = -rs * LOG2E, rs2 = rs * rs;
;                 u32x4 w;
; #pragma unroll
;                 for (int n = 0; n < 2; ++n) {
;                     const pg8::f32x4 g = acc[ai][0][m][n], up = acc[ai][1][m][n];
;                     float o4[4];
; #pragma unroll
;                     for (int k = 0; k < 4; ++k) o4[k] = (g[k] * up[k]) * (rs2 * __builtin_amdgcn_rcpf(1.f + __builtin_amdgcn_exp2f(g[k] * c1)));
;                     w[2 * n] = cvtpk(o4[0], o4[1]); w[2 * n + 1] = cvtpk(o4[2], o4[3]);
;                 }
;                 *(u32x4*)(O + (size_t)row * FF + col0) = w;
;             }
	v_fmamk_f32 v80, v174, 0x3a000000, v150
	v_mul_f32_e32 v81, 0x4b800000, v80
	v_cmp_gt_f32_e32 vcc, s45, v80
	v_pk_mul_f32 v[82:83], v[82:83], v[84:85]
	s_nop 0
	v_cndmask_b32_e32 v80, v80, v81, vcc
	v_cvt_pk_bf16_f32 v91, v82, v83
	v_rsq_f32_e32 v82, v80
	v_mad_i64_i32 v[80:81], s[4:5], v170, s46, v[120:121]
	v_lshl_add_u64 v[80:81], v[80:81], 0, v[106:107]
	global_store_dwordx4 v[80:81], v[88:91], off
	v_mul_f32_e32 v80, 0x45800000, v82
	v_cndmask_b32_e32 v80, v82, v80, vcc
	v_mul_f32_e32 v81, 0xbfb8aa3b, v80
	v_mul_f32_e32 v82, v76, v81
	v_mul_f32_e32 v83, v77, v81
	v_exp_f32_e32 v82, v82
	v_exp_f32_e32 v83, v83
	v_mul_f32_e32 v84, v78, v81
	v_mul_f32_e32 v85, v79, v81
	v_exp_f32_e32 v84, v84
	v_exp_f32_e32 v85, v85
	v_add_f32_e32 v82, 1.0, v82
	v_add_f32_e32 v83, 1.0, v83
	v_rcp_f32_e32 v82, v82
	v_rcp_f32_e32 v83, v83
	v_add_f32_e32 v78, 1.0, v84
	v_add_f32_e32 v79, 1.0, v85
	v_rcp_f32_e32 v78, v78
	v_rcp_f32_e32 v79, v79
	v_mul_f32_e32 v80, v80, v80
	v_pk_mul_f32 v[76:77], v[80:81], v[82:83] op_sel_hi:[0,1]
	v_pk_mul_f32 v[72:73], v[72:73], v[76:77]
	v_pk_mul_f32 v[76:77], v[80:81], v[78:79] op_sel_hi:[0,1]
	v_cvt_pk_bf16_f32 v72, v72, v73
	v_mul_f32_e32 v73, v68, v81
	v_pk_mul_f32 v[74:75], v[74:75], v[76:77]
	v_exp_f32_e32 v76, v73
	v_mul_f32_e32 v73, v69, v81
	v_exp_f32_e32 v77, v73
	v_cvt_pk_bf16_f32 v73, v74, v75
	v_add_f32_e32 v74, 1.0, v76
	v_mul_f32_e32 v76, v70, v81
	v_add_f32_e32 v75, 1.0, v77
	v_mul_f32_e32 v77, v71, v81
	v_exp_f32_e32 v76, v76
	v_exp_f32_e32 v77, v77
	v_rcp_f32_e32 v74, v74
	v_rcp_f32_e32 v75, v75
	v_add_f32_e32 v70, 1.0, v76
	v_add_f32_e32 v71, 1.0, v77
	v_rcp_f32_e32 v70, v70
	v_rcp_f32_e32 v71, v71
	v_pk_mul_f32 v[68:69], v[80:81], v[74:75] op_sel_hi:[0,1]
	v_pk_mul_f32 v[64:65], v[64:65], v[68:69]
	v_pk_mul_f32 v[68:69], v[80:81], v[70:71] op_sel_hi:[0,1]
	v_cvt_pk_bf16_f32 v74, v64, v65
	v_fmamk_f32 v64, v175, 0x3a000000, v150
	v_mul_f32_e32 v65, 0x4b800000, v64
	v_cmp_gt_f32_e32 vcc, s45, v64
	v_pk_mul_f32 v[66:67], v[66:67], v[68:69]
	s_nop 0
	v_cndmask_b32_e32 v64, v64, v65, vcc
	v_cvt_pk_bf16_f32 v75, v66, v67
	v_rsq_f32_e32 v66, v64
	v_mad_i64_i32 v[64:65], s[4:5], v171, s46, v[120:121]
	v_lshl_add_u64 v[64:65], v[64:65], 0, v[106:107]
	global_store_dwordx4 v[64:65], v[72:75], off
	v_mul_f32_e32 v64, 0x45800000, v66
	v_cndmask_b32_e32 v64, v66, v64, vcc
	v_mul_f32_e32 v65, 0xbfb8aa3b, v64
	v_mul_f32_e32 v66, v60, v65
	v_mul_f32_e32 v67, v61, v65
	v_exp_f32_e32 v66, v66
	v_exp_f32_e32 v67, v67
	v_mul_f32_e32 v68, v62, v65
	v_mul_f32_e32 v69, v63, v65
	v_exp_f32_e32 v68, v68
	v_exp_f32_e32 v69, v69
	v_add_f32_e32 v66, 1.0, v66
	v_add_f32_e32 v67, 1.0, v67
	v_rcp_f32_e32 v66, v66
	v_rcp_f32_e32 v67, v67
	v_add_f32_e32 v62, 1.0, v68
	v_add_f32_e32 v63, 1.0, v69
	v_rcp_f32_e32 v62, v62
	v_rcp_f32_e32 v63, v63
	v_mul_f32_e32 v64, v64, v64
	v_pk_mul_f32 v[60:61], v[64:65], v[66:67] op_sel_hi:[0,1]
	v_pk_mul_f32 v[56:57], v[56:57], v[60:61]
	v_pk_mul_f32 v[60:61], v[64:65], v[62:63] op_sel_hi:[0,1]
	v_cvt_pk_bf16_f32 v56, v56, v57
	v_mul_f32_e32 v57, v52, v65
	v_pk_mul_f32 v[58:59], v[58:59], v[60:61]
	v_exp_f32_e32 v60, v57
	v_mul_f32_e32 v57, v53, v65
	v_exp_f32_e32 v61, v57
	v_cvt_pk_bf16_f32 v57, v58, v59
	v_add_f32_e32 v58, 1.0, v60
	v_mul_f32_e32 v60, v54, v65
	v_add_f32_e32 v59, 1.0, v61
	v_mul_f32_e32 v61, v55, v65
	v_exp_f32_e32 v60, v60
	v_exp_f32_e32 v61, v61
	v_rcp_f32_e32 v58, v58
	v_rcp_f32_e32 v59, v59
	v_add_f32_e32 v54, 1.0, v60
	v_add_f32_e32 v55, 1.0, v61
	v_rcp_f32_e32 v54, v54
	v_rcp_f32_e32 v55, v55
	v_pk_mul_f32 v[52:53], v[64:65], v[58:59] op_sel_hi:[0,1]
	v_pk_mul_f32 v[48:49], v[48:49], v[52:53]
	v_pk_mul_f32 v[52:53], v[64:65], v[54:55] op_sel_hi:[0,1]
	v_cvt_pk_bf16_f32 v58, v48, v49
	v_fmamk_f32 v48, v176, 0x3a000000, v150
	v_mul_f32_e32 v49, 0x4b800000, v48
	v_cmp_gt_f32_e32 vcc, s45, v48
	v_pk_mul_f32 v[50:51], v[50:51], v[52:53]
	s_nop 0
	v_cndmask_b32_e32 v48, v48, v49, vcc
	v_cvt_pk_bf16_f32 v59, v50, v51
	v_rsq_f32_e32 v50, v48
	v_mad_i64_i32 v[48:49], s[4:5], v172, s46, v[120:121]
	v_lshl_add_u64 v[48:49], v[48:49], 0, v[106:107]
	global_store_dwordx4 v[48:49], v[56:59], off
	v_mul_f32_e32 v48, 0x45800000, v50
	v_cndmask_b32_e32 v48, v50, v48, vcc
	v_mul_f32_e32 v49, 0xbfb8aa3b, v48
	v_mul_f32_e32 v50, v44, v49
	v_mul_f32_e32 v51, v45, v49
	v_exp_f32_e32 v50, v50
	v_exp_f32_e32 v51, v51
	v_mul_f32_e32 v52, v46, v49
	v_mul_f32_e32 v53, v47, v49
	v_exp_f32_e32 v52, v52
	v_exp_f32_e32 v53, v53
	v_add_f32_e32 v50, 1.0, v50
	v_add_f32_e32 v51, 1.0, v51
	v_rcp_f32_e32 v50, v50
	v_rcp_f32_e32 v51, v51
	v_add_f32_e32 v46, 1.0, v52
	v_add_f32_e32 v47, 1.0, v53
	v_rcp_f32_e32 v46, v46
	v_rcp_f32_e32 v47, v47
	v_mul_f32_e32 v48, v48, v48
	v_pk_mul_f32 v[44:45], v[48:49], v[50:51] op_sel_hi:[0,1]
	v_pk_mul_f32 v[40:41], v[40:41], v[44:45]
; #define PG8_BAR __builtin_amdgcn_s_barrier()
; __device__ __forceinline__ unsigned cvtpk(float lo, float hi) { f32x2_t v = {lo, hi}; bf16x2_t b = __builtin_convertvector(v, bf16x2_t); return __builtin_bit_cast(unsigned, b); }
; template <class Epi, class Sched, bool ALIGN_EPI = false, bool SP2 = false>
; __device__ __forceinline__ void gemm_phase(PG8_LAS unsigned char* lds, const Gemm g, const Sched& S, const Epi& E) {
;     ...
;         if (!has_next) break;
; #pragma unroll
;         for (int a = 0; a < 2; ++a)
; #pragma unroll
;             for (int b = 0; b < 2; ++b)
; #pragma unroll
;                 for (int m = 0; m < 4; ++m)
; #pragma unroll
;                     for (int n = 0; n < 2; ++n) acc[a][b][m][n] = (f32x4){0.f, 0.f, 0.f, 0.f};
;         cur = nxt; cA = nA; cB = nB; ++ui;
;         if constexpr (ALIGN_EPI) { if (wr == 1) PG8_BAR; }
;     __device__ __forceinline__ void operator()(const pg8::f32x4 (&acc)[2][2][4][2], const pg8::Unit& u, int wr, int wc, int fr, int fq) const {
;     ...
;         for (int ai = 0; ai < 2; ++ai)
; #pragma unroll
;             for (int m = 0; m < 4; ++m) {
;                 const int row = row0 + ai * 128 + m * 16;
;                 const float rs = rsqrtf(rsv[ai][m] * (1.f / DM) + EPS), c1 = -rs * LOG2E, rs2 = rs * rs;
;                 u32x4 w;
; #pragma unroll
;                 for (int n = 0; n < 2; ++n) {
;                     const pg8::f32x4 g = acc[ai][0][m][n], up = acc[ai][1][m][n];
;                     float o4[4];
; #pragma unroll
;                     for (int k = 0; k < 4; ++k) o4[k] = (g[k] * up[k]) * (rs2 * __builtin_amdgcn_rcpf(1.f + __builtin_amdgcn_exp2f(g[k] * c1)));
;                     w[2 * n] = cvtpk(o4[0], o4[1]); w[2 * n + 1] = cvtpk(o4[2], o4[3]);
;                 }
;                 *(u32x4*)(O + (size_t)row * FF + col0) = w;
;             }
	v_pk_mul_f32 v[44:45], v[48:49], v[46:47] op_sel_hi:[0,1]
	v_cvt_pk_bf16_f32 v40, v40, v41
	v_mul_f32_e32 v41, v36, v49
	v_pk_mul_f32 v[42:43], v[42:43], v[44:45]
	v_exp_f32_e32 v44, v41
	v_mul_f32_e32 v41, v37, v49
	v_exp_f32_e32 v45, v41
	v_cvt_pk_bf16_f32 v41, v42, v43
	v_add_f32_e32 v42, 1.0, v44
	v_mul_f32_e32 v44, v38, v49
	v_add_f32_e32 v43, 1.0, v45
	v_mul_f32_e32 v45, v39, v49
	v_exp_f32_e32 v44, v44
	v_exp_f32_e32 v45, v45
	v_rcp_f32_e32 v42, v42
	v_rcp_f32_e32 v43, v43
	v_add_f32_e32 v38, 1.0, v44
	v_add_f32_e32 v39, 1.0, v45
	v_rcp_f32_e32 v38, v38
	v_rcp_f32_e32 v39, v39
	v_pk_mul_f32 v[36:37], v[48:49], v[42:43] op_sel_hi:[0,1]
	v_pk_mul_f32 v[32:33], v[32:33], v[36:37]
	v_pk_mul_f32 v[36:37], v[48:49], v[38:39] op_sel_hi:[0,1]
	v_cvt_pk_bf16_f32 v42, v32, v33
	v_fmamk_f32 v32, v126, 0x3a000000, v150
	v_mul_f32_e32 v33, 0x4b800000, v32
	v_cmp_gt_f32_e32 vcc, s45, v32
	v_pk_mul_f32 v[34:35], v[34:35], v[36:37]
	s_nop 0
	v_cndmask_b32_e32 v32, v32, v33, vcc
	v_cvt_pk_bf16_f32 v43, v34, v35
	v_rsq_f32_e32 v34, v32
	v_mad_i64_i32 v[32:33], s[4:5], v125, s46, v[120:121]
	v_lshl_add_u64 v[32:33], v[32:33], 0, v[106:107]
	global_store_dwordx4 v[32:33], v[40:43], off
	v_mul_f32_e32 v32, 0x45800000, v34
	v_cndmask_b32_e32 v32, v34, v32, vcc
	v_mul_f32_e32 v33, 0xbfb8aa3b, v32
	v_mul_f32_e32 v34, v28, v33
	v_mul_f32_e32 v35, v29, v33
	v_exp_f32_e32 v34, v34
	v_exp_f32_e32 v35, v35
	v_mul_f32_e32 v36, v30, v33
	v_mul_f32_e32 v37, v31, v33
	v_exp_f32_e32 v36, v36
	v_exp_f32_e32 v37, v37
	v_add_f32_e32 v34, 1.0, v34
	v_add_f32_e32 v35, 1.0, v35
	v_rcp_f32_e32 v34, v34
	v_rcp_f32_e32 v35, v35
	v_add_f32_e32 v30, 1.0, v36
	v_add_f32_e32 v31, 1.0, v37
	v_rcp_f32_e32 v30, v30
	v_rcp_f32_e32 v31, v31
	v_mul_f32_e32 v32, v32, v32
	v_pk_mul_f32 v[28:29], v[32:33], v[34:35] op_sel_hi:[0,1]
	v_pk_mul_f32 v[24:25], v[24:25], v[28:29]
	v_pk_mul_f32 v[28:29], v[32:33], v[30:31] op_sel_hi:[0,1]
	v_cvt_pk_bf16_f32 v24, v24, v25
	v_mul_f32_e32 v25, v20, v33
	v_pk_mul_f32 v[26:27], v[26:27], v[28:29]
	v_exp_f32_e32 v28, v25
	v_mul_f32_e32 v25, v21, v33
	v_exp_f32_e32 v29, v25
	v_cvt_pk_bf16_f32 v25, v26, v27
	v_add_f32_e32 v26, 1.0, v28
	v_mul_f32_e32 v28, v22, v33
	v_add_f32_e32 v27, 1.0, v29
	v_mul_f32_e32 v29, v23, v33
	v_exp_f32_e32 v28, v28
	v_exp_f32_e32 v29, v29
	v_rcp_f32_e32 v26, v26
	v_rcp_f32_e32 v27, v27
	v_add_f32_e32 v22, 1.0, v28
	v_add_f32_e32 v23, 1.0, v29
	v_rcp_f32_e32 v22, v22
	v_rcp_f32_e32 v23, v23
	v_pk_mul_f32 v[20:21], v[32:33], v[26:27] op_sel_hi:[0,1]
	v_pk_mul_f32 v[16:17], v[16:17], v[20:21]
	v_pk_mul_f32 v[20:21], v[32:33], v[22:23] op_sel_hi:[0,1]
	v_cvt_pk_bf16_f32 v26, v16, v17
	v_fmamk_f32 v16, v124, 0x3a000000, v150
	v_mul_f32_e32 v17, 0x4b800000, v16
	v_cmp_gt_f32_e32 vcc, s45, v16
	v_pk_mul_f32 v[18:19], v[18:19], v[20:21]
	s_nop 0
	v_cndmask_b32_e32 v16, v16, v17, vcc
	v_cvt_pk_bf16_f32 v27, v18, v19
	v_rsq_f32_e32 v18, v16
	v_mad_i64_i32 v[16:17], s[4:5], v123, s46, v[120:121]
	v_lshl_add_u64 v[16:17], v[16:17], 0, v[106:107]
	global_store_dwordx4 v[16:17], v[24:27], off
	v_mul_f32_e32 v16, 0x45800000, v18
	v_cndmask_b32_e32 v16, v18, v16, vcc
	v_mul_f32_e32 v17, 0xbfb8aa3b, v16
	v_mul_f32_e32 v18, v12, v17
	v_mul_f32_e32 v19, v13, v17
	v_exp_f32_e32 v18, v18
	v_exp_f32_e32 v19, v19
	v_mul_f32_e32 v20, v14, v17
	v_mul_f32_e32 v21, v15, v17
	v_exp_f32_e32 v20, v20
	v_exp_f32_e32 v21, v21
	v_add_f32_e32 v18, 1.0, v18
	v_add_f32_e32 v19, 1.0, v19
	v_rcp_f32_e32 v18, v18
	v_rcp_f32_e32 v19, v19
	v_add_f32_e32 v14, 1.0, v20
	v_add_f32_e32 v15, 1.0, v21
	v_rcp_f32_e32 v14, v14
	v_rcp_f32_e32 v15, v15
	v_mul_f32_e32 v16, v16, v16
	v_pk_mul_f32 v[12:13], v[16:17], v[18:19] op_sel_hi:[0,1]
	v_pk_mul_f32 v[8:9], v[8:9], v[12:13]
	v_pk_mul_f32 v[12:13], v[16:17], v[14:15] op_sel_hi:[0,1]
	v_cvt_pk_bf16_f32 v8, v8, v9
	v_mul_f32_e32 v9, v4, v17
	v_pk_mul_f32 v[10:11], v[10:11], v[12:13]
	v_exp_f32_e32 v12, v9
	v_mul_f32_e32 v9, v5, v17
	v_exp_f32_e32 v13, v9
	v_cvt_pk_bf16_f32 v9, v10, v11
	v_add_f32_e32 v10, 1.0, v12
	v_mul_f32_e32 v12, v6, v17
	v_add_f32_e32 v11, 1.0, v13
	v_mul_f32_e32 v13, v7, v17
	v_exp_f32_e32 v12, v12
	v_exp_f32_e32 v13, v13
	v_rcp_f32_e32 v10, v10
	v_rcp_f32_e32 v11, v11
	v_add_f32_e32 v6, 1.0, v12
	v_add_f32_e32 v7, 1.0, v13
	v_rcp_f32_e32 v6, v6
	v_rcp_f32_e32 v7, v7
	v_pk_mul_f32 v[4:5], v[16:17], v[10:11] op_sel_hi:[0,1]
	v_pk_mul_f32 v[0:1], v[0:1], v[4:5]
	s_andn2_b64 vcc, exec, s[2:3]
	v_pk_mul_f32 v[4:5], v[16:17], v[6:7] op_sel_hi:[0,1]
	v_pk_mul_f32 v[2:3], v[2:3], v[4:5]
	v_cvt_pk_bf16_f32 v10, v0, v1
	v_mad_i64_i32 v[0:1], s[4:5], v122, s46, v[120:121]
	v_cvt_pk_bf16_f32 v11, v2, v3
	v_lshl_add_u64 v[0:1], v[0:1], 0, v[106:107]
	s_mov_b64 s[2:3], -1
	global_store_dwordx4 v[0:1], v[8:11], off
	s_cbranch_vccnz .LBB0_200
	s_andn2_b64 vcc, exec, s[8:9]
	s_cbranch_vccnz .LBB0_199
	s_barrier
	s_branch .LBB0_199

; __global__ void __launch_bounds__(512, 2) fwd_megakernel(Args a) {
	.amdhsa_kernel _Z14fwd_megakernel4Args
		.amdhsa_group_segment_fixed_size 0
		.amdhsa_private_segment_fixed_size 0
		.amdhsa_kernarg_size 512
		.amdhsa_user_sgpr_count 2
		.amdhsa_user_sgpr_dispatch_ptr 0
		.amdhsa_user_sgpr_queue_ptr 0
		.amdhsa_user_sgpr_kernarg_segment_ptr 1
		.amdhsa_user_sgpr_dispatch_id 0
		.amdhsa_user_sgpr_kernarg_preload_length 0
		.amdhsa_user_sgpr_kernarg_preload_offset 0
		.amdhsa_user_sgpr_private_segment_size 0
		.amdhsa_uses_dynamic_stack 0
		.amdhsa_enable_private_segment 0
		.amdhsa_system_sgpr_workgroup_id_x 1
		.amdhsa_system_sgpr_workgroup_id_y 0
		.amdhsa_system_sgpr_workgroup_id_z 0
		.amdhsa_system_sgpr_workgroup_info 0
		.amdhsa_system_vgpr_workitem_id 2
		.amdhsa_next_free_vgpr 256
		.amdhsa_next_free_sgpr 102
		.amdhsa_accum_offset 256
		.amdhsa_reserve_vcc 1
		.amdhsa_float_round_mode_32 0
		.amdhsa_float_round_mode_16_64 0
		.amdhsa_float_denorm_mode_32 3
		.amdhsa_float_denorm_mode_16_64 3
		.amdhsa_dx10_clamp 1
		.amdhsa_ieee_mode 1
		.amdhsa_fp16_overflow 0
		.amdhsa_tg_split 0
		.amdhsa_exception_fp_ieee_invalid_op 0
		.amdhsa_exception_fp_denorm_src 0
		.amdhsa_exception_fp_ieee_div_zero 0
		.amdhsa_exception_fp_ieee_overflow 0
		.amdhsa_exception_fp_ieee_underflow 0
		.amdhsa_exception_fp_ieee_inexact 0
		.amdhsa_exception_int_div_zero 0
	.end_amdhsa_kernel

; __global__ void __launch_bounds__(512, 2) fwd_megakernel(Args a) {
amdhsa.kernels:
  - .agpr_count:     0
    .args:
      - .offset:         0
        .size:           256
        .value_kind:     by_value
      - .offset:         256
        .size:           4
        .value_kind:     hidden_block_count_x
      - .offset:         260
        .size:           4
        .value_kind:     hidden_block_count_y
      - .offset:         264
        .size:           4
        .value_kind:     hidden_block_count_z
      - .offset:         268
        .size:           2
        .value_kind:     hidden_group_size_x
      - .offset:         270
        .size:           2
        .value_kind:     hidden_group_size_y
      - .offset:         272
        .size:           2
        .value_kind:     hidden_group_size_z
      - .offset:         274
        .size:           2
        .value_kind:     hidden_remainder_x
      - .offset:         276
        .size:           2
        .value_kind:     hidden_remainder_y
      - .offset:         278
        .size:           2
        .value_kind:     hidden_remainder_z
      - .offset:         296
        .size:           8
        .value_kind:     hidden_global_offset_x
      - .offset:         304
        .size:           8
        .value_kind:     hidden_global_offset_y
      - .offset:         312
        .size:           8
        .value_kind:     hidden_global_offset_z
      - .offset:         320
        .size:           2
        .value_kind:     hidden_grid_dims
      - .offset:         344
        .size:           8
        .value_kind:     hidden_multigrid_sync_arg
      - .offset:         376
        .size:           4
        .value_kind:     hidden_dynamic_lds_size
    .group_segment_fixed_size: 0
    .kernarg_segment_align: 8
    .kernarg_segment_size: 512
    .language:       OpenCL C
    .language_version:
      - 2
      - 0
    .max_flat_workgroup_size: 512
    .name:           _Z14fwd_megakernel4Args
    .private_segment_fixed_size: 0
    .sgpr_count:     108
    .sgpr_spill_count: 38
    .symbol:         _Z14fwd_megakernel4Args.kd
    .uniform_work_group_size: 1
    .uses_dynamic_stack: false
    .vgpr_count:     256
    .vgpr_spill_count: 0
    .wavefront_size: 64
